# LayerNorm row loads marked nt (rows are read once per phase)
# speedup vs baseline: 1.0055x; 1.0055x over previous
.LBB0_670:
	v_add_co_u32_e32 v136, vcc, 0xffffc3f8, v100
	s_nop 1
	v_addc_co_u32_e32 v137, vcc, -1, v101, vcc
	v_add_co_u32_e32 v138, vcc, 0xffffd3f8, v100
	s_nop 1
	v_addc_co_u32_e32 v139, vcc, -1, v101, vcc
	v_add_co_u32_e32 v140, vcc, 0xffffe3f8, v100
	s_nop 1
	v_addc_co_u32_e32 v141, vcc, -1, v101, vcc
	v_add_co_u32_e32 v142, vcc, 0xfffff3f8, v100
	s_nop 1
	v_addc_co_u32_e32 v143, vcc, -1, v101, vcc
	global_load_dwordx4 v[34:37], v[136:137], off nt
	global_load_dwordx4 v[38:41], v[136:137], off offset:1024 nt
	global_load_dwordx4 v[42:45], v[136:137], off offset:2048 nt
	global_load_dwordx4 v[46:49], v[136:137], off offset:3072 nt
	global_load_dwordx4 v[50:53], v[138:139], off nt
	global_load_dwordx4 v[54:57], v[138:139], off offset:1024 nt
	global_load_dwordx4 v[58:61], v[138:139], off offset:2048 nt
	global_load_dwordx4 v[62:65], v[138:139], off offset:3072 nt
	global_load_dwordx4 v[66:69], v[140:141], off nt
	global_load_dwordx4 v[70:73], v[140:141], off offset:1024 nt
	global_load_dwordx4 v[74:77], v[140:141], off offset:2048 nt
	global_load_dwordx4 v[78:81], v[140:141], off offset:3072 nt
	global_load_dwordx4 v[82:85], v[142:143], off nt
	global_load_dwordx4 v[86:89], v[142:143], off offset:1024 nt
	global_load_dwordx4 v[90:93], v[142:143], off offset:2048 nt
	global_load_dwordx4 v[94:97], v[142:143], off offset:3072 nt
	s_mov_b32 s10, 0x3727c5ac
	s_mov_b32 s5, 0x800000
	s_waitcnt vmcnt(12)
	v_add_f32_e32 v0, v34, v35
	v_add_f32_e32 v0, v0, v36
	v_add_f32_e32 v0, v0, v37
	v_add_f32_e32 v144, v38, v39
	v_add_f32_e32 v144, v144, v40
	v_add_f32_e32 v0, 0, v0
	v_add_f32_e32 v144, v144, v41
	v_add_f32_e32 v0, v0, v144
	v_add_f32_e32 v144, v42, v43
	v_add_f32_e32 v144, v144, v44
	v_add_f32_e32 v144, v144, v45
	v_add_f32_e32 v0, v0, v144
	v_add_f32_e32 v144, v46, v47
	v_add_f32_e32 v144, v144, v48
	v_add_f32_e32 v144, v144, v49
	v_add_f32_e32 v0, v0, v144
	ds_swizzle_b32 v144, v0 offset:swizzle(SWAP,1)
	s_waitcnt lgkmcnt(0)
	v_add_f32_e32 v0, v0, v144
	ds_swizzle_b32 v144, v0 offset:swizzle(SWAP,2)
	s_waitcnt lgkmcnt(0)
	v_add_f32_e32 v0, v0, v144
	ds_swizzle_b32 v144, v0 offset:swizzle(SWAP,4)
	s_waitcnt lgkmcnt(0)
	v_add_f32_e32 v0, v0, v144
	ds_swizzle_b32 v144, v0 offset:swizzle(SWAP,8)
	s_waitcnt lgkmcnt(0)
	v_add_f32_e32 v0, v0, v144
	ds_swizzle_b32 v144, v0 offset:swizzle(SWAP,16)
	s_waitcnt lgkmcnt(0)
	v_add_f32_e32 v0, v0, v144
	s_waitcnt vmcnt(8)
	v_add_f32_e32 v144, v50, v51
	v_add_f32_e32 v144, v144, v52
	v_add_f32_e32 v144, v144, v53
	v_add_f32_e32 v145, 0, v144
	v_add_f32_e32 v144, v54, v55
	v_add_f32_e32 v144, v144, v56
	v_add_f32_e32 v144, v144, v57
	v_add_f32_e32 v145, v145, v144
	v_add_f32_e32 v144, v58, v59
	v_add_f32_e32 v144, v144, v60
	v_add_f32_e32 v144, v144, v61
	v_add_f32_e32 v145, v145, v144
	v_add_f32_e32 v144, v62, v63
	v_add_f32_e32 v144, v144, v64
	v_add_f32_e32 v144, v144, v65
	v_add_f32_e32 v102, v145, v144
	s_waitcnt vmcnt(4)
	v_add_f32_e32 v144, v66, v67
	v_add_f32_e32 v144, v144, v68
	v_add_f32_e32 v144, v144, v69
	v_add_f32_e32 v145, 0, v144
	v_add_f32_e32 v144, v70, v71
	v_add_f32_e32 v144, v144, v72
	v_add_f32_e32 v144, v144, v73
	v_add_f32_e32 v145, v145, v144
	v_add_f32_e32 v144, v74, v75
	v_add_f32_e32 v144, v144, v76
	v_add_f32_e32 v144, v144, v77
	v_add_f32_e32 v145, v145, v144
	v_add_f32_e32 v144, v78, v79
	v_add_f32_e32 v144, v144, v80
	v_add_f32_e32 v144, v144, v81
	v_add_f32_e32 v104, v145, v144
	s_waitcnt vmcnt(0)
	v_add_f32_e32 v144, v82, v83
	v_add_f32_e32 v144, v144, v84
	v_add_f32_e32 v144, v144, v85
	v_add_f32_e32 v145, 0, v144
	v_add_f32_e32 v144, v86, v87
	v_add_f32_e32 v144, v144, v88
	v_add_f32_e32 v144, v144, v89
	v_add_f32_e32 v145, v145, v144
	v_add_f32_e32 v144, v90, v91
	v_add_f32_e32 v144, v144, v92
	v_add_f32_e32 v144, v144, v93
	v_add_f32_e32 v105, v145, v144
	v_add_f32_e32 v106, v94, v95
	v_add_f32_e32 v106, v106, v96
	v_add_f32_e32 v106, v106, v97
	v_add_f32_e32 v105, v105, v106
	v_mov_b32_e32 v106, v0
	s_nop 1
	v_permlane32_swap_b32_e32 v0, v106
	v_add_f32_e32 v0, v0, v106
	ds_swizzle_b32 v106, v102 offset:swizzle(SWAP,1)
	v_mul_f32_e32 v0, 0x3a800000, v0
	v_pk_add_f32 v[130:131], v[34:35], v[0:1] op_sel_hi:[1,0] neg_lo:[0,1] neg_hi:[0,1]
	v_pk_add_f32 v[126:127], v[38:39], v[0:1] op_sel_hi:[1,0] neg_lo:[0,1] neg_hi:[0,1]
	v_pk_add_f32 v[132:133], v[36:37], v[0:1] op_sel_hi:[1,0] neg_lo:[0,1] neg_hi:[0,1]
	s_waitcnt lgkmcnt(0)
	v_add_f32_e32 v102, v102, v106
	ds_swizzle_b32 v106, v102 offset:swizzle(SWAP,2)
	v_mov_b32_e32 v36, v131
	v_mov_b32_e32 v37, v127
	v_pk_add_f32 v[128:129], v[40:41], v[0:1] op_sel_hi:[1,0] neg_lo:[0,1] neg_hi:[0,1]
	v_mov_b32_e32 v34, v130
	s_waitcnt lgkmcnt(0)
	v_add_f32_e32 v102, v102, v106
	ds_swizzle_b32 v106, v102 offset:swizzle(SWAP,4)
	v_mov_b32_e32 v35, v126
	v_pk_mul_f32 v[36:37], v[36:37], v[36:37]
	v_pk_add_f32 v[122:123], v[42:43], v[0:1] op_sel_hi:[1,0] neg_lo:[0,1] neg_hi:[0,1]
	v_pk_fma_f32 v[34:35], v[34:35], v[34:35], v[36:37]
	s_waitcnt lgkmcnt(0)
	v_add_f32_e32 v102, v102, v106
	ds_swizzle_b32 v106, v102 offset:swizzle(SWAP,8)
	v_mov_b32_e32 v36, v132
	v_mov_b32_e32 v37, v128
	v_pk_add_f32 v[114:115], v[46:47], v[0:1] op_sel_hi:[1,0] neg_lo:[0,1] neg_hi:[0,1]
	v_pk_fma_f32 v[34:35], v[36:37], v[36:37], v[34:35]
	s_waitcnt lgkmcnt(0)
	v_add_f32_e32 v102, v102, v106
	ds_swizzle_b32 v106, v102 offset:swizzle(SWAP,16)
	v_mov_b32_e32 v36, v133
	v_mov_b32_e32 v37, v129
	v_mov_b32_e32 v38, v115
	v_mov_b32_e32 v39, v123
	s_waitcnt lgkmcnt(0)
	v_add_f32_e32 v102, v102, v106
	v_mov_b32_e32 v106, v102
	v_pk_fma_f32 v[34:35], v[36:37], v[36:37], v[34:35]
	s_nop 0
	v_permlane32_swap_b32_e32 v102, v106
	v_add_f32_e32 v102, v102, v106
	ds_swizzle_b32 v106, v104 offset:swizzle(SWAP,1)
	v_pk_add_f32 v[124:125], v[44:45], v[0:1] op_sel_hi:[1,0] neg_lo:[0,1] neg_hi:[0,1]
	v_pk_add_f32 v[116:117], v[48:49], v[0:1] op_sel_hi:[1,0] neg_lo:[0,1] neg_hi:[0,1]
	v_mov_b32_e32 v36, v114
	v_mov_b32_e32 v37, v122
	s_waitcnt lgkmcnt(0)
	v_add_f32_e32 v104, v104, v106
	ds_swizzle_b32 v106, v104 offset:swizzle(SWAP,2)
	v_pk_mul_f32 v[38:39], v[38:39], v[38:39]
	v_mul_f32_e32 v102, 0x3a800000, v102
	v_pk_fma_f32 v[36:37], v[36:37], v[36:37], v[38:39]
	v_mov_b32_e32 v38, v116
	s_waitcnt lgkmcnt(0)
	v_add_f32_e32 v104, v104, v106
	ds_swizzle_b32 v106, v104 offset:swizzle(SWAP,4)
	v_mov_b32_e32 v39, v124
	v_pk_fma_f32 v[36:37], v[38:39], v[38:39], v[36:37]
	v_mov_b32_e32 v38, v117
	v_mov_b32_e32 v39, v125
	s_waitcnt lgkmcnt(0)
	v_add_f32_e32 v104, v104, v106
	ds_swizzle_b32 v106, v104 offset:swizzle(SWAP,8)
	v_pk_fma_f32 v[36:37], v[38:39], v[38:39], v[36:37]
	v_add_f32_e32 v34, v34, v35
	v_add_f32_e32 v34, v37, v34
	v_pk_add_f32 v[118:119], v[50:51], v[102:103] op_sel_hi:[1,0] neg_lo:[0,1] neg_hi:[0,1]
	s_waitcnt lgkmcnt(0)
	v_add_f32_e32 v104, v104, v106
	ds_swizzle_b32 v106, v104 offset:swizzle(SWAP,16)
	v_pk_add_f32 v[110:111], v[54:55], v[102:103] op_sel_hi:[1,0] neg_lo:[0,1] neg_hi:[0,1]
	v_pk_add_f32 v[120:121], v[52:53], v[102:103] op_sel_hi:[1,0] neg_lo:[0,1] neg_hi:[0,1]
	v_mov_b32_e32 v37, v111
	v_pk_add_f32 v[112:113], v[56:57], v[102:103] op_sel_hi:[1,0] neg_lo:[0,1] neg_hi:[0,1]
	s_waitcnt lgkmcnt(0)
	v_add_f32_e32 v104, v104, v106
	v_mov_b32_e32 v106, v104
	v_mov_b32_e32 v35, v110
	s_nop 0
	v_permlane32_swap_b32_e32 v104, v106
	v_add_f32_e32 v104, v104, v106
	ds_swizzle_b32 v106, v105 offset:swizzle(SWAP,1)
	v_pk_add_f32 v[62:63], v[62:63], v[102:103] op_sel_hi:[1,0] neg_lo:[0,1] neg_hi:[0,1]
	v_pk_add_f32 v[108:109], v[60:61], v[102:103] op_sel_hi:[1,0] neg_lo:[0,1] neg_hi:[0,1]
	v_mov_b32_e32 v38, v63
	v_pk_add_f32 v[64:65], v[64:65], v[102:103] op_sel_hi:[1,0] neg_lo:[0,1] neg_hi:[0,1]
	s_waitcnt lgkmcnt(0)
	v_add_f32_e32 v105, v105, v106
	ds_swizzle_b32 v106, v105 offset:swizzle(SWAP,2)
	v_mul_f32_e32 v104, 0x3a800000, v104
	s_waitcnt lgkmcnt(0)
	v_add_f32_e32 v105, v105, v106
	ds_swizzle_b32 v106, v105 offset:swizzle(SWAP,4)
	s_waitcnt lgkmcnt(0)
	v_add_f32_e32 v105, v105, v106
	ds_swizzle_b32 v106, v105 offset:swizzle(SWAP,8)
	s_waitcnt lgkmcnt(0)
	v_add_f32_e32 v105, v105, v106
	ds_swizzle_b32 v106, v105 offset:swizzle(SWAP,16)
	s_waitcnt lgkmcnt(0)
	v_add_f32_e32 v105, v105, v106
	v_mov_b32_e32 v106, v105
	s_nop 1
	v_permlane32_swap_b32_e32 v105, v106
	v_add_f32_e32 v105, v105, v106
	v_mul_f32_e32 v134, 0x3a800000, v105
	v_add_f32_e32 v105, v36, v34
	v_mov_b32_e32 v36, v119
	v_mov_b32_e32 v34, v118
	v_pk_mul_f32 v[36:37], v[36:37], v[36:37]
	v_pk_add_f32 v[106:107], v[58:59], v[102:103] op_sel_hi:[1,0] neg_lo:[0,1] neg_hi:[0,1]
	v_pk_fma_f32 v[34:35], v[34:35], v[34:35], v[36:37]
	v_mov_b32_e32 v36, v120
	v_mov_b32_e32 v37, v112
	v_pk_fma_f32 v[34:35], v[36:37], v[36:37], v[34:35]
	v_mov_b32_e32 v36, v121
	v_mov_b32_e32 v37, v113
	v_mov_b32_e32 v39, v107
	v_pk_fma_f32 v[34:35], v[36:37], v[36:37], v[34:35]
	v_mov_b32_e32 v36, v62
	v_mov_b32_e32 v37, v106
	v_pk_mul_f32 v[38:39], v[38:39], v[38:39]
	v_add_f32_e32 v34, v34, v35
	v_pk_fma_f32 v[36:37], v[36:37], v[36:37], v[38:39]
	v_mov_b32_e32 v38, v64
	v_mov_b32_e32 v39, v108
	v_pk_fma_f32 v[36:37], v[38:39], v[38:39], v[36:37]
	v_mov_b32_e32 v38, v65
	v_mov_b32_e32 v39, v109
	v_pk_fma_f32 v[36:37], v[38:39], v[38:39], v[36:37]
	v_pk_add_f32 v[66:67], v[66:67], v[104:105] op_sel_hi:[1,0] neg_lo:[0,1] neg_hi:[0,1]
	v_add_f32_e32 v34, v37, v34
	v_pk_add_f32 v[58:59], v[70:71], v[104:105] op_sel_hi:[1,0] neg_lo:[0,1] neg_hi:[0,1]
	v_add_f32_e32 v135, v36, v34
	v_mov_b32_e32 v36, v67
	v_mov_b32_e32 v37, v59
	v_pk_add_f32 v[68:69], v[68:69], v[104:105] op_sel_hi:[1,0] neg_lo:[0,1] neg_hi:[0,1]
	v_pk_add_f32 v[60:61], v[72:73], v[104:105] op_sel_hi:[1,0] neg_lo:[0,1] neg_hi:[0,1]
	v_mov_b32_e32 v34, v66
	v_mov_b32_e32 v35, v58
	v_pk_mul_f32 v[36:37], v[36:37], v[36:37]
	v_pk_add_f32 v[54:55], v[74:75], v[104:105] op_sel_hi:[1,0] neg_lo:[0,1] neg_hi:[0,1]
	v_pk_fma_f32 v[34:35], v[34:35], v[34:35], v[36:37]
	v_mov_b32_e32 v36, v68
	v_mov_b32_e32 v37, v60
	v_pk_add_f32 v[46:47], v[78:79], v[104:105] op_sel_hi:[1,0] neg_lo:[0,1] neg_hi:[0,1]
	v_pk_fma_f32 v[34:35], v[36:37], v[36:37], v[34:35]
	v_mov_b32_e32 v36, v69
	v_mov_b32_e32 v37, v61
	v_mov_b32_e32 v38, v47
	v_mov_b32_e32 v39, v55
	v_pk_fma_f32 v[34:35], v[36:37], v[36:37], v[34:35]
	v_pk_add_f32 v[56:57], v[76:77], v[104:105] op_sel_hi:[1,0] neg_lo:[0,1] neg_hi:[0,1]
	v_pk_add_f32 v[48:49], v[80:81], v[104:105] op_sel_hi:[1,0] neg_lo:[0,1] neg_hi:[0,1]
	v_mov_b32_e32 v36, v46
	v_mov_b32_e32 v37, v54
	v_pk_mul_f32 v[38:39], v[38:39], v[38:39]
	v_add_f32_e32 v34, v34, v35
	v_pk_fma_f32 v[36:37], v[36:37], v[36:37], v[38:39]
	v_mov_b32_e32 v38, v48
	v_mov_b32_e32 v39, v56
	v_pk_fma_f32 v[36:37], v[38:39], v[38:39], v[36:37]
	v_mov_b32_e32 v38, v49
	v_mov_b32_e32 v39, v57
	v_pk_fma_f32 v[36:37], v[38:39], v[38:39], v[36:37]
	v_pk_add_f32 v[50:51], v[82:83], v[134:135] op_sel_hi:[1,0] neg_lo:[0,1] neg_hi:[0,1]
	v_add_f32_e32 v34, v37, v34
	v_pk_add_f32 v[42:43], v[86:87], v[134:135] op_sel_hi:[1,0] neg_lo:[0,1] neg_hi:[0,1]
	v_add_f32_e32 v76, v36, v34
	v_mov_b32_e32 v36, v51
	v_mov_b32_e32 v37, v43
	v_pk_add_f32 v[52:53], v[84:85], v[134:135] op_sel_hi:[1,0] neg_lo:[0,1] neg_hi:[0,1]
	v_pk_add_f32 v[44:45], v[88:89], v[134:135] op_sel_hi:[1,0] neg_lo:[0,1] neg_hi:[0,1]
	v_mov_b32_e32 v34, v50
	v_mov_b32_e32 v35, v42
	v_pk_mul_f32 v[36:37], v[36:37], v[36:37]
	v_pk_add_f32 v[38:39], v[90:91], v[134:135] op_sel_hi:[1,0] neg_lo:[0,1] neg_hi:[0,1]
	v_pk_fma_f32 v[34:35], v[34:35], v[34:35], v[36:37]
	v_mov_b32_e32 v36, v52
	v_mov_b32_e32 v37, v44
	v_pk_fma_f32 v[34:35], v[36:37], v[36:37], v[34:35]
	v_mov_b32_e32 v36, v53
	v_mov_b32_e32 v37, v45
	v_pk_fma_f32 v[70:71], v[36:37], v[36:37], v[34:35]
	v_pk_add_f32 v[34:35], v[94:95], v[134:135] op_sel_hi:[1,0] neg_lo:[0,1] neg_hi:[0,1]
	v_mov_b32_e32 v75, v39
	v_mov_b32_e32 v74, v35
	v_pk_add_f32 v[40:41], v[92:93], v[134:135] op_sel_hi:[1,0] neg_lo:[0,1] neg_hi:[0,1]
	v_pk_add_f32 v[36:37], v[96:97], v[134:135] op_sel_hi:[1,0] neg_lo:[0,1] neg_hi:[0,1]
	v_mov_b32_e32 v72, v34
	v_mov_b32_e32 v73, v38
	v_pk_mul_f32 v[74:75], v[74:75], v[74:75]
	v_add_f32_e32 v70, v70, v71
	v_pk_fma_f32 v[72:73], v[72:73], v[72:73], v[74:75]
	v_mov_b32_e32 v74, v36
	v_mov_b32_e32 v75, v40
	v_pk_fma_f32 v[72:73], v[74:75], v[74:75], v[72:73]
	v_mov_b32_e32 v74, v37
	v_mov_b32_e32 v75, v41
	v_pk_fma_f32 v[72:73], v[74:75], v[74:75], v[72:73]
	v_mov_b64_e32 v[74:75], s[10:11]
	v_add_f32_e32 v70, v73, v70
	v_add_f32_e32 v78, v72, v70
	ds_swizzle_b32 v70, v105 offset:swizzle(SWAP,1)
	s_mov_b32 s10, 0x3a800000
	s_waitcnt lgkmcnt(0)
	v_add_f32_e32 v70, v105, v70
	ds_swizzle_b32 v71, v70 offset:swizzle(SWAP,2)
	s_waitcnt lgkmcnt(0)
	v_add_f32_e32 v70, v70, v71
	ds_swizzle_b32 v71, v70 offset:swizzle(SWAP,4)
	s_waitcnt lgkmcnt(0)
	v_add_f32_e32 v70, v70, v71
	ds_swizzle_b32 v71, v70 offset:swizzle(SWAP,8)
	s_waitcnt lgkmcnt(0)
	v_add_f32_e32 v70, v70, v71
	ds_swizzle_b32 v71, v70 offset:swizzle(SWAP,16)
	s_waitcnt lgkmcnt(0)
	v_add_f32_e32 v71, v70, v71
	ds_swizzle_b32 v70, v135 offset:swizzle(SWAP,1)
	v_mov_b32_e32 v73, v71
	s_waitcnt lgkmcnt(0)
	v_add_f32_e32 v70, v135, v70
	ds_swizzle_b32 v72, v70 offset:swizzle(SWAP,2)
	v_permlane32_swap_b32_e32 v71, v73
	s_waitcnt lgkmcnt(0)
	v_add_f32_e32 v70, v70, v72
	ds_swizzle_b32 v72, v70 offset:swizzle(SWAP,4)
	s_waitcnt lgkmcnt(0)
	v_add_f32_e32 v70, v70, v72
	ds_swizzle_b32 v72, v70 offset:swizzle(SWAP,8)
	s_waitcnt lgkmcnt(0)
	v_add_f32_e32 v70, v70, v72
	ds_swizzle_b32 v72, v70 offset:swizzle(SWAP,16)
	s_waitcnt lgkmcnt(0)
	v_add_f32_e32 v70, v70, v72
	v_mov_b32_e32 v72, v70
	s_nop 1
	v_permlane32_swap_b32_e32 v70, v72
	v_pk_add_f32 v[70:71], v[70:71], v[72:73]
	s_nop 0
	v_pk_fma_f32 v[70:71], v[70:71], s[10:11], v[74:75] op_sel_hi:[1,0,0]
	s_nop 0
	v_mul_f32_e32 v72, 0x4b800000, v71
	v_cmp_gt_f32_e64 s[48:49], s5, v71
	v_cmp_gt_f32_e32 vcc, s5, v70
	s_nop 0
	v_cndmask_b32_e64 v71, v71, v72, s[48:49]
	v_rsq_f32_e32 v71, v71
	s_nop 0
	v_mul_f32_e32 v72, 0x45800000, v71
	v_cndmask_b32_e64 v72, v71, v72, s[48:49]
	v_mul_f32_e32 v71, 0x4b800000, v70
	v_cndmask_b32_e32 v70, v70, v71, vcc
	v_rsq_f32_e32 v70, v70
	s_nop 0
	v_mul_f32_e32 v71, 0x45800000, v70
	v_cndmask_b32_e32 v70, v70, v71, vcc
	ds_swizzle_b32 v71, v76 offset:swizzle(SWAP,1)
	s_waitcnt lgkmcnt(0)
	v_add_f32_e32 v71, v76, v71
	ds_swizzle_b32 v73, v71 offset:swizzle(SWAP,2)
	s_waitcnt lgkmcnt(0)
	v_add_f32_e32 v71, v71, v73
	ds_swizzle_b32 v73, v71 offset:swizzle(SWAP,4)
	s_waitcnt lgkmcnt(0)
	v_add_f32_e32 v71, v71, v73
	ds_swizzle_b32 v73, v71 offset:swizzle(SWAP,8)
	s_waitcnt lgkmcnt(0)
	v_add_f32_e32 v71, v71, v73
	ds_swizzle_b32 v73, v71 offset:swizzle(SWAP,16)
	s_waitcnt lgkmcnt(0)
	v_add_f32_e32 v77, v71, v73
	ds_swizzle_b32 v71, v78 offset:swizzle(SWAP,1)
	v_mov_b32_e32 v79, v77
	s_waitcnt lgkmcnt(0)
	v_add_f32_e32 v71, v78, v71
	ds_swizzle_b32 v73, v71 offset:swizzle(SWAP,2)
	v_permlane32_swap_b32_e32 v77, v79
	s_waitcnt lgkmcnt(0)
	v_add_f32_e32 v71, v71, v73
	ds_swizzle_b32 v73, v71 offset:swizzle(SWAP,4)
	s_waitcnt lgkmcnt(0)
	v_add_f32_e32 v71, v71, v73
	ds_swizzle_b32 v73, v71 offset:swizzle(SWAP,8)
	s_waitcnt lgkmcnt(0)
	v_add_f32_e32 v71, v71, v73
	ds_swizzle_b32 v73, v71 offset:swizzle(SWAP,16)
	s_waitcnt lgkmcnt(0)
	v_add_f32_e32 v76, v71, v73
	v_mov_b32_e32 v78, v76
	s_nop 1
	v_permlane32_swap_b32_e32 v76, v78
	v_pk_add_f32 v[76:77], v[76:77], v[78:79]
	s_nop 0
	v_pk_fma_f32 v[74:75], v[76:77], s[10:11], v[74:75] op_sel_hi:[1,0,0]
	s_nop 0
	v_mul_f32_e32 v71, 0x4b800000, v75
	v_cmp_gt_f32_e64 s[48:49], s5, v75
	v_cmp_gt_f32_e32 vcc, s5, v74
	s_nop 0
	v_cndmask_b32_e64 v71, v75, v71, s[48:49]
	v_rsq_f32_e32 v71, v71
	s_nop 0
	v_mul_f32_e32 v73, 0x45800000, v71
	v_cndmask_b32_e64 v76, v71, v73, s[48:49]
	v_mul_f32_e32 v71, 0x4b800000, v74
	v_cndmask_b32_e32 v71, v74, v71, vcc
	v_rsq_f32_e32 v71, v71
	s_nop 0
	v_mul_f32_e32 v73, 0x45800000, v71
	v_cndmask_b32_e32 v74, v71, v73, vcc
	s_and_saveexec_b64 s[48:49], s[40:41]
	s_cbranch_execz .LBB0_669
	v_cndmask_b32_e64 v71, v134, v104, s[46:47]
	v_cndmask_b32_e64 v71, v71, v102, s[44:45]
	v_cndmask_b32_e64 v78, v71, v0, s[42:43]
	v_cndmask_b32_e64 v0, v74, v76, s[46:47]
	v_add_u32_e32 v80, s4, v103
	v_cndmask_b32_e64 v0, v0, v70, s[44:45]
	v_ashrrev_i32_e32 v81, 31, v80
	v_cndmask_b32_e64 v79, v0, v72, s[42:43]
	v_lshl_add_u64 v[80:81], v[80:81], 3, s[8:9]
	global_store_dwordx2 v[80:81], v[78:79], off
	s_branch .LBB0_669

.LBB0_725:
	v_add_co_u32_e32 v136, vcc, s90, v100
	s_nop 1
	v_addc_co_u32_e32 v137, vcc, -1, v101, vcc
	v_add_co_u32_e32 v138, vcc, s89, v100
	s_nop 1
	v_addc_co_u32_e32 v139, vcc, -1, v101, vcc
	v_add_co_u32_e32 v140, vcc, s94, v100
	s_nop 1
	v_addc_co_u32_e32 v141, vcc, -1, v101, vcc
	v_add_co_u32_e32 v142, vcc, 0xffffc3f8, v100
	s_nop 1
	v_addc_co_u32_e32 v143, vcc, -1, v101, vcc
	global_load_dwordx4 v[46:49], v[136:137], off nt
	global_load_dwordx4 v[42:45], v[136:137], off offset:1024 nt
	global_load_dwordx4 v[38:41], v[136:137], off offset:2048 nt
	global_load_dwordx4 v[34:37], v[136:137], off offset:3072 nt
	global_load_dwordx4 v[62:65], v[138:139], off nt
	global_load_dwordx4 v[58:61], v[138:139], off offset:1024 nt
	global_load_dwordx4 v[54:57], v[138:139], off offset:2048 nt
	global_load_dwordx4 v[50:53], v[138:139], off offset:3072 nt
	global_load_dwordx4 v[78:81], v[140:141], off nt
	global_load_dwordx4 v[74:77], v[140:141], off offset:1024 nt
	global_load_dwordx4 v[70:73], v[140:141], off offset:2048 nt
	global_load_dwordx4 v[66:69], v[140:141], off offset:3072 nt
	global_load_dwordx4 v[94:97], v[142:143], off nt
	global_load_dwordx4 v[90:93], v[142:143], off offset:1024 nt
	global_load_dwordx4 v[86:89], v[142:143], off offset:2048 nt
	global_load_dwordx4 v[82:85], v[142:143], off offset:3072 nt
	s_mov_b32 s10, 0x3727c5ac
	s_mov_b32 s5, 0x800000
	s_waitcnt vmcnt(12)
	v_add_f32_e32 v145, v46, v47
	v_add_f32_e32 v145, v145, v48
	v_add_f32_e32 v145, v145, v49
	v_add_f32_e32 v145, 0, v145
	v_add_f32_e32 v144, v42, v43
	v_add_f32_e32 v144, v144, v44
	v_add_f32_e32 v144, v144, v45
	v_add_f32_e32 v145, v145, v144
	v_add_f32_e32 v144, v38, v39
	v_add_f32_e32 v144, v144, v40
	v_add_f32_e32 v144, v144, v41
	v_add_f32_e32 v145, v145, v144
	v_add_f32_e32 v144, v34, v35
	v_add_f32_e32 v144, v144, v36
	v_add_f32_e32 v144, v144, v37
	v_add_f32_e32 v105, v145, v144
	s_waitcnt vmcnt(8)
	v_add_f32_e32 v145, v62, v63
	v_add_f32_e32 v145, v145, v64
	v_add_f32_e32 v145, v145, v65
	v_add_f32_e32 v145, 0, v145
	v_add_f32_e32 v144, v58, v59
	v_add_f32_e32 v144, v144, v60
	v_add_f32_e32 v144, v144, v61
	v_add_f32_e32 v145, v145, v144
	v_add_f32_e32 v144, v54, v55
	v_add_f32_e32 v144, v144, v56
	v_add_f32_e32 v144, v144, v57
	v_add_f32_e32 v145, v145, v144
	v_add_f32_e32 v144, v50, v51
	v_add_f32_e32 v144, v144, v52
	v_add_f32_e32 v144, v144, v53
	v_add_f32_e32 v104, v145, v144
	s_waitcnt vmcnt(4)
	v_add_f32_e32 v145, v78, v79
	v_add_f32_e32 v145, v145, v80
	v_add_f32_e32 v145, v145, v81
	v_add_f32_e32 v145, 0, v145
	v_add_f32_e32 v144, v74, v75
	v_add_f32_e32 v144, v144, v76
	v_add_f32_e32 v144, v144, v77
	v_add_f32_e32 v145, v145, v144
	v_add_f32_e32 v144, v70, v71
	v_add_f32_e32 v144, v144, v72
	v_add_f32_e32 v144, v144, v73
	v_add_f32_e32 v145, v145, v144
	v_add_f32_e32 v144, v66, v67
	v_add_f32_e32 v144, v144, v68
	v_add_f32_e32 v144, v144, v69
	v_add_f32_e32 v102, v145, v144
	s_waitcnt vmcnt(0)
	v_add_f32_e32 v145, v94, v95
	v_add_f32_e32 v145, v145, v96
	v_add_f32_e32 v145, v145, v97
	v_add_f32_e32 v145, 0, v145
	v_add_f32_e32 v144, v90, v91
	v_add_f32_e32 v144, v144, v92
	v_add_f32_e32 v144, v144, v93
	v_add_f32_e32 v145, v145, v144
	v_add_f32_e32 v144, v86, v87
	v_add_f32_e32 v144, v144, v88
	v_add_f32_e32 v144, v144, v89
	v_add_f32_e32 v145, v145, v144
	v_add_f32_e32 v144, v82, v83
	v_add_f32_e32 v144, v144, v84
	v_add_f32_e32 v144, v144, v85
	v_add_f32_e32 v0, v145, v144
	ds_swizzle_b32 v106, v0 offset:swizzle(SWAP,1)
	s_waitcnt lgkmcnt(0)
	v_add_f32_e32 v0, v0, v106
	ds_swizzle_b32 v106, v0 offset:swizzle(SWAP,2)
	s_waitcnt lgkmcnt(0)
	v_add_f32_e32 v0, v0, v106
	ds_swizzle_b32 v106, v0 offset:swizzle(SWAP,4)
	s_waitcnt lgkmcnt(0)
	v_add_f32_e32 v0, v0, v106
	ds_swizzle_b32 v106, v0 offset:swizzle(SWAP,8)
	s_waitcnt lgkmcnt(0)
	v_add_f32_e32 v0, v0, v106
	ds_swizzle_b32 v106, v0 offset:swizzle(SWAP,16)
	s_waitcnt lgkmcnt(0)
	v_add_f32_e32 v0, v0, v106
	v_mov_b32_e32 v106, v0
	s_nop 1
	v_permlane32_swap_b32_e32 v0, v106
	v_add_f32_e32 v0, v0, v106
	ds_swizzle_b32 v106, v102 offset:swizzle(SWAP,1)
	v_mul_f32_e32 v0, 0x3a800000, v0
	v_pk_add_f32 v[108:109], v[94:95], v[0:1] op_sel_hi:[1,0] neg_lo:[0,1] neg_hi:[0,1]
	v_pk_add_f32 v[94:95], v[92:93], v[0:1] op_sel_hi:[1,0] neg_lo:[0,1] neg_hi:[0,1]
	v_mov_b32_e32 v92, v109
	s_waitcnt lgkmcnt(0)
	v_add_f32_e32 v102, v102, v106
	ds_swizzle_b32 v106, v102 offset:swizzle(SWAP,2)
	s_waitcnt lgkmcnt(0)
	v_add_f32_e32 v102, v102, v106
	ds_swizzle_b32 v106, v102 offset:swizzle(SWAP,4)
	s_waitcnt lgkmcnt(0)
	v_add_f32_e32 v102, v102, v106
	ds_swizzle_b32 v106, v102 offset:swizzle(SWAP,8)
	s_waitcnt lgkmcnt(0)
	v_add_f32_e32 v102, v102, v106
	ds_swizzle_b32 v106, v102 offset:swizzle(SWAP,16)
	s_waitcnt lgkmcnt(0)
	v_add_f32_e32 v102, v102, v106
	v_mov_b32_e32 v106, v102
	s_nop 1
	v_permlane32_swap_b32_e32 v102, v106
	v_add_f32_e32 v102, v102, v106
	ds_swizzle_b32 v106, v104 offset:swizzle(SWAP,1)
	v_mul_f32_e32 v102, 0x3a800000, v102
	s_waitcnt lgkmcnt(0)
	v_add_f32_e32 v104, v104, v106
	ds_swizzle_b32 v106, v104 offset:swizzle(SWAP,2)
	s_waitcnt lgkmcnt(0)
	v_add_f32_e32 v104, v104, v106
	ds_swizzle_b32 v106, v104 offset:swizzle(SWAP,4)
	s_waitcnt lgkmcnt(0)
	v_add_f32_e32 v104, v104, v106
	ds_swizzle_b32 v106, v104 offset:swizzle(SWAP,8)
	s_waitcnt lgkmcnt(0)
	v_add_f32_e32 v104, v104, v106
	ds_swizzle_b32 v106, v104 offset:swizzle(SWAP,16)
	s_waitcnt lgkmcnt(0)
	v_add_f32_e32 v104, v104, v106
	v_mov_b32_e32 v106, v104
	s_nop 1
	v_permlane32_swap_b32_e32 v104, v106
	v_add_f32_e32 v104, v104, v106
	ds_swizzle_b32 v106, v105 offset:swizzle(SWAP,1)
	v_mul_f32_e32 v104, 0x3a800000, v104
	s_waitcnt lgkmcnt(0)
	v_add_f32_e32 v105, v105, v106
	ds_swizzle_b32 v106, v105 offset:swizzle(SWAP,2)
	s_waitcnt lgkmcnt(0)
	v_add_f32_e32 v105, v105, v106
	ds_swizzle_b32 v106, v105 offset:swizzle(SWAP,4)
	s_waitcnt lgkmcnt(0)
	v_add_f32_e32 v105, v105, v106
	ds_swizzle_b32 v106, v105 offset:swizzle(SWAP,8)
	s_waitcnt lgkmcnt(0)
	v_add_f32_e32 v105, v105, v106
	ds_swizzle_b32 v106, v105 offset:swizzle(SWAP,16)
	s_waitcnt lgkmcnt(0)
	v_add_f32_e32 v105, v105, v106
	v_mov_b32_e32 v106, v105
	s_nop 1
	v_permlane32_swap_b32_e32 v105, v106
	v_add_f32_e32 v105, v105, v106
	v_pk_add_f32 v[106:107], v[96:97], v[0:1] op_sel_hi:[1,0] neg_lo:[0,1] neg_hi:[0,1]
	v_pk_add_f32 v[96:97], v[90:91], v[0:1] op_sel_hi:[1,0] neg_lo:[0,1] neg_hi:[0,1]
	v_mov_b32_e32 v90, v108
	v_mov_b32_e32 v93, v97
	v_mov_b32_e32 v91, v96
	v_pk_mul_f32 v[92:93], v[92:93], v[92:93]
	v_mul_f32_e32 v110, 0x3a800000, v105
	v_pk_fma_f32 v[90:91], v[90:91], v[90:91], v[92:93]
	v_mov_b32_e32 v92, v106
	v_mov_b32_e32 v93, v94
	v_pk_fma_f32 v[90:91], v[92:93], v[92:93], v[90:91]
	v_mov_b32_e32 v92, v107
	v_mov_b32_e32 v93, v95
	v_pk_fma_f32 v[112:113], v[92:93], v[92:93], v[90:91]
	v_pk_add_f32 v[92:93], v[86:87], v[0:1] op_sel_hi:[1,0] neg_lo:[0,1] neg_hi:[0,1]
	v_pk_add_f32 v[90:91], v[88:89], v[0:1] op_sel_hi:[1,0] neg_lo:[0,1] neg_hi:[0,1]
	v_pk_add_f32 v[88:89], v[82:83], v[0:1] op_sel_hi:[1,0] neg_lo:[0,1] neg_hi:[0,1]
	v_pk_add_f32 v[86:87], v[84:85], v[0:1] op_sel_hi:[1,0] neg_lo:[0,1] neg_hi:[0,1]
	v_mov_b32_e32 v84, v89
	v_mov_b32_e32 v85, v93
	v_mov_b32_e32 v82, v88
	v_mov_b32_e32 v83, v92
	v_pk_mul_f32 v[84:85], v[84:85], v[84:85]
	s_nop 0
	v_pk_fma_f32 v[82:83], v[82:83], v[82:83], v[84:85]
	v_mov_b32_e32 v84, v86
	v_mov_b32_e32 v85, v90
	v_pk_fma_f32 v[82:83], v[84:85], v[84:85], v[82:83]
	v_mov_b32_e32 v84, v87
	v_mov_b32_e32 v85, v91
	v_pk_fma_f32 v[82:83], v[84:85], v[84:85], v[82:83]
	v_add_f32_e32 v84, v112, v113
	v_add_f32_e32 v83, v83, v84
	v_add_f32_e32 v105, v82, v83
	v_pk_add_f32 v[84:85], v[78:79], v[102:103] op_sel_hi:[1,0] neg_lo:[0,1] neg_hi:[0,1]
	v_pk_add_f32 v[82:83], v[80:81], v[102:103] op_sel_hi:[1,0] neg_lo:[0,1] neg_hi:[0,1]
	v_pk_add_f32 v[80:81], v[74:75], v[102:103] op_sel_hi:[1,0] neg_lo:[0,1] neg_hi:[0,1]
	v_pk_add_f32 v[78:79], v[76:77], v[102:103] op_sel_hi:[1,0] neg_lo:[0,1] neg_hi:[0,1]
	v_mov_b32_e32 v76, v85
	v_mov_b32_e32 v77, v81
	v_mov_b32_e32 v74, v84
	v_mov_b32_e32 v75, v80
	v_pk_mul_f32 v[76:77], v[76:77], v[76:77]
	s_nop 0
	v_pk_fma_f32 v[74:75], v[74:75], v[74:75], v[76:77]
	v_mov_b32_e32 v76, v82
	v_mov_b32_e32 v77, v78
	v_pk_fma_f32 v[74:75], v[76:77], v[76:77], v[74:75]
	v_mov_b32_e32 v76, v83
	v_mov_b32_e32 v77, v79
	v_pk_fma_f32 v[112:113], v[76:77], v[76:77], v[74:75]
	v_pk_add_f32 v[76:77], v[70:71], v[102:103] op_sel_hi:[1,0] neg_lo:[0,1] neg_hi:[0,1]
	v_pk_add_f32 v[74:75], v[72:73], v[102:103] op_sel_hi:[1,0] neg_lo:[0,1] neg_hi:[0,1]
	v_pk_add_f32 v[72:73], v[66:67], v[102:103] op_sel_hi:[1,0] neg_lo:[0,1] neg_hi:[0,1]
	v_pk_add_f32 v[70:71], v[68:69], v[102:103] op_sel_hi:[1,0] neg_lo:[0,1] neg_hi:[0,1]
	v_mov_b32_e32 v68, v73
	v_mov_b32_e32 v69, v77
	v_mov_b32_e32 v66, v72
	v_mov_b32_e32 v67, v76
	v_pk_mul_f32 v[68:69], v[68:69], v[68:69]
	s_nop 0
	v_pk_fma_f32 v[66:67], v[66:67], v[66:67], v[68:69]
	v_mov_b32_e32 v68, v70
	v_mov_b32_e32 v69, v74
	v_pk_fma_f32 v[66:67], v[68:69], v[68:69], v[66:67]
	v_mov_b32_e32 v68, v71
	v_mov_b32_e32 v69, v75
	v_pk_fma_f32 v[66:67], v[68:69], v[68:69], v[66:67]
	v_add_f32_e32 v68, v112, v113
	v_add_f32_e32 v67, v67, v68
	v_add_f32_e32 v111, v66, v67
	v_pk_add_f32 v[68:69], v[62:63], v[104:105] op_sel_hi:[1,0] neg_lo:[0,1] neg_hi:[0,1]
	v_pk_add_f32 v[66:67], v[64:65], v[104:105] op_sel_hi:[1,0] neg_lo:[0,1] neg_hi:[0,1]
	v_pk_add_f32 v[64:65], v[58:59], v[104:105] op_sel_hi:[1,0] neg_lo:[0,1] neg_hi:[0,1]
	v_pk_add_f32 v[62:63], v[60:61], v[104:105] op_sel_hi:[1,0] neg_lo:[0,1] neg_hi:[0,1]
	v_mov_b32_e32 v60, v69
	v_mov_b32_e32 v61, v65
	v_mov_b32_e32 v58, v68
	v_mov_b32_e32 v59, v64
	v_pk_mul_f32 v[60:61], v[60:61], v[60:61]
	s_nop 0
	v_pk_fma_f32 v[58:59], v[58:59], v[58:59], v[60:61]
	v_mov_b32_e32 v60, v66
	v_mov_b32_e32 v61, v62
	v_pk_fma_f32 v[58:59], v[60:61], v[60:61], v[58:59]
	v_mov_b32_e32 v60, v67
	v_mov_b32_e32 v61, v63
	v_pk_fma_f32 v[112:113], v[60:61], v[60:61], v[58:59]
	v_pk_add_f32 v[60:61], v[54:55], v[104:105] op_sel_hi:[1,0] neg_lo:[0,1] neg_hi:[0,1]
	v_pk_add_f32 v[58:59], v[56:57], v[104:105] op_sel_hi:[1,0] neg_lo:[0,1] neg_hi:[0,1]
	v_pk_add_f32 v[56:57], v[50:51], v[104:105] op_sel_hi:[1,0] neg_lo:[0,1] neg_hi:[0,1]
	v_pk_add_f32 v[54:55], v[52:53], v[104:105] op_sel_hi:[1,0] neg_lo:[0,1] neg_hi:[0,1]
	v_mov_b32_e32 v52, v57
	v_mov_b32_e32 v53, v61
	v_mov_b32_e32 v50, v56
	v_mov_b32_e32 v51, v60
	v_pk_mul_f32 v[52:53], v[52:53], v[52:53]
	s_nop 0
	v_pk_fma_f32 v[50:51], v[50:51], v[50:51], v[52:53]
	v_mov_b32_e32 v52, v54
	v_mov_b32_e32 v53, v58
	v_pk_fma_f32 v[50:51], v[52:53], v[52:53], v[50:51]
	v_mov_b32_e32 v52, v55
	v_mov_b32_e32 v53, v59
	v_pk_fma_f32 v[50:51], v[52:53], v[52:53], v[50:51]
	v_add_f32_e32 v52, v112, v113
	v_add_f32_e32 v51, v51, v52
	v_add_f32_e32 v114, v50, v51
	v_pk_add_f32 v[52:53], v[46:47], v[110:111] op_sel_hi:[1,0] neg_lo:[0,1] neg_hi:[0,1]
	v_pk_add_f32 v[50:51], v[48:49], v[110:111] op_sel_hi:[1,0] neg_lo:[0,1] neg_hi:[0,1]
	v_pk_add_f32 v[48:49], v[42:43], v[110:111] op_sel_hi:[1,0] neg_lo:[0,1] neg_hi:[0,1]
	v_pk_add_f32 v[46:47], v[44:45], v[110:111] op_sel_hi:[1,0] neg_lo:[0,1] neg_hi:[0,1]
	v_mov_b32_e32 v44, v53
	v_mov_b32_e32 v45, v49
	v_mov_b32_e32 v42, v52
	v_mov_b32_e32 v43, v48
	v_pk_mul_f32 v[44:45], v[44:45], v[44:45]
	s_nop 0
	v_pk_fma_f32 v[42:43], v[42:43], v[42:43], v[44:45]
	v_mov_b32_e32 v44, v50
	v_mov_b32_e32 v45, v46
	v_pk_fma_f32 v[42:43], v[44:45], v[44:45], v[42:43]
	v_mov_b32_e32 v44, v51
	v_mov_b32_e32 v45, v47
	v_pk_fma_f32 v[112:113], v[44:45], v[44:45], v[42:43]
	v_pk_add_f32 v[44:45], v[38:39], v[110:111] op_sel_hi:[1,0] neg_lo:[0,1] neg_hi:[0,1]
	v_pk_add_f32 v[42:43], v[40:41], v[110:111] op_sel_hi:[1,0] neg_lo:[0,1] neg_hi:[0,1]
	v_pk_add_f32 v[40:41], v[34:35], v[110:111] op_sel_hi:[1,0] neg_lo:[0,1] neg_hi:[0,1]
	v_pk_add_f32 v[38:39], v[36:37], v[110:111] op_sel_hi:[1,0] neg_lo:[0,1] neg_hi:[0,1]
	v_mov_b32_e32 v36, v41
	v_mov_b32_e32 v37, v45
	v_mov_b32_e32 v34, v40
	v_mov_b32_e32 v35, v44
	v_pk_mul_f32 v[36:37], v[36:37], v[36:37]
	s_nop 0
	v_pk_fma_f32 v[34:35], v[34:35], v[34:35], v[36:37]
	v_mov_b32_e32 v36, v38
	v_mov_b32_e32 v37, v42
	v_pk_fma_f32 v[34:35], v[36:37], v[36:37], v[34:35]
	v_mov_b32_e32 v36, v39
	v_mov_b32_e32 v37, v43
	v_pk_fma_f32 v[34:35], v[36:37], v[36:37], v[34:35]
	v_add_f32_e32 v36, v112, v113
	v_add_f32_e32 v35, v35, v36
	v_add_f32_e32 v113, v34, v35
	ds_swizzle_b32 v34, v105 offset:swizzle(SWAP,1)
	s_waitcnt lgkmcnt(0)
	v_add_f32_e32 v34, v105, v34
	ds_swizzle_b32 v35, v34 offset:swizzle(SWAP,2)
	s_waitcnt lgkmcnt(0)
	v_add_f32_e32 v34, v34, v35
	ds_swizzle_b32 v35, v34 offset:swizzle(SWAP,4)
	s_waitcnt lgkmcnt(0)
	v_add_f32_e32 v34, v34, v35
	ds_swizzle_b32 v35, v34 offset:swizzle(SWAP,8)
	s_waitcnt lgkmcnt(0)
	v_add_f32_e32 v34, v34, v35
	ds_swizzle_b32 v35, v34 offset:swizzle(SWAP,16)
	s_waitcnt lgkmcnt(0)
	v_add_f32_e32 v35, v34, v35
	ds_swizzle_b32 v34, v111 offset:swizzle(SWAP,1)
	v_mov_b32_e32 v37, v35
	s_waitcnt lgkmcnt(0)
	v_add_f32_e32 v34, v111, v34
	ds_swizzle_b32 v36, v34 offset:swizzle(SWAP,2)
	v_permlane32_swap_b32_e32 v35, v37
	s_waitcnt lgkmcnt(0)
	v_add_f32_e32 v34, v34, v36
	ds_swizzle_b32 v36, v34 offset:swizzle(SWAP,4)
	s_waitcnt lgkmcnt(0)
	v_add_f32_e32 v34, v34, v36
	ds_swizzle_b32 v36, v34 offset:swizzle(SWAP,8)
	s_waitcnt lgkmcnt(0)
	v_add_f32_e32 v34, v34, v36
	ds_swizzle_b32 v36, v34 offset:swizzle(SWAP,16)
	s_waitcnt lgkmcnt(0)
	v_add_f32_e32 v34, v34, v36
	v_mov_b32_e32 v36, v34
	s_nop 1
	v_permlane32_swap_b32_e32 v34, v36
	v_pk_add_f32 v[36:37], v[34:35], v[36:37]
	v_mov_b64_e32 v[34:35], s[10:11]
	s_mov_b32 s10, 0x3a800000
	v_pk_fma_f32 v[36:37], v[36:37], s[10:11], v[34:35] op_sel_hi:[1,0,0]
	s_nop 0
	v_mul_f32_e32 v105, 0x4b800000, v37
	v_cmp_gt_f32_e64 s[48:49], s5, v37
	v_cmp_gt_f32_e32 vcc, s5, v36
	s_nop 0
	v_cndmask_b32_e64 v37, v37, v105, s[48:49]
	v_rsq_f32_e32 v37, v37
	s_nop 0
	v_mul_f32_e32 v105, 0x45800000, v37
	v_cndmask_b32_e64 v116, v37, v105, s[48:49]
	v_mul_f32_e32 v37, 0x4b800000, v36
	v_cndmask_b32_e32 v36, v36, v37, vcc
	v_rsq_f32_e32 v36, v36
	s_nop 0
	v_mul_f32_e32 v37, 0x45800000, v36
	v_cndmask_b32_e32 v112, v36, v37, vcc
	ds_swizzle_b32 v36, v114 offset:swizzle(SWAP,1)
	s_waitcnt lgkmcnt(0)
	v_add_f32_e32 v36, v114, v36
	ds_swizzle_b32 v37, v36 offset:swizzle(SWAP,2)
	s_waitcnt lgkmcnt(0)
	v_add_f32_e32 v36, v36, v37
	ds_swizzle_b32 v37, v36 offset:swizzle(SWAP,4)
	s_waitcnt lgkmcnt(0)
	v_add_f32_e32 v36, v36, v37
	ds_swizzle_b32 v37, v36 offset:swizzle(SWAP,8)
	s_waitcnt lgkmcnt(0)
	v_add_f32_e32 v36, v36, v37
	ds_swizzle_b32 v37, v36 offset:swizzle(SWAP,16)
	s_waitcnt lgkmcnt(0)
	v_add_f32_e32 v37, v36, v37
	ds_swizzle_b32 v36, v113 offset:swizzle(SWAP,1)
	v_mov_b32_e32 v115, v37
	s_waitcnt lgkmcnt(0)
	v_add_f32_e32 v36, v113, v36
	ds_swizzle_b32 v105, v36 offset:swizzle(SWAP,2)
	v_permlane32_swap_b32_e32 v37, v115
	s_waitcnt lgkmcnt(0)
	v_add_f32_e32 v36, v36, v105
	ds_swizzle_b32 v105, v36 offset:swizzle(SWAP,4)
	s_waitcnt lgkmcnt(0)
	v_add_f32_e32 v36, v36, v105
	ds_swizzle_b32 v105, v36 offset:swizzle(SWAP,8)
	s_waitcnt lgkmcnt(0)
	v_add_f32_e32 v36, v36, v105
	ds_swizzle_b32 v105, v36 offset:swizzle(SWAP,16)
	s_waitcnt lgkmcnt(0)
	v_add_f32_e32 v36, v36, v105
	v_mov_b32_e32 v114, v36
	s_nop 1
	v_permlane32_swap_b32_e32 v36, v114
	v_pk_add_f32 v[36:37], v[36:37], v[114:115]
	s_nop 0
	v_pk_fma_f32 v[34:35], v[36:37], s[10:11], v[34:35] op_sel_hi:[1,0,0]
	s_nop 0
	v_mul_f32_e32 v36, 0x4b800000, v35
	v_cmp_gt_f32_e64 s[48:49], s5, v35
	v_cmp_gt_f32_e32 vcc, s5, v34
	s_nop 0
	v_cndmask_b32_e64 v35, v35, v36, s[48:49]
	v_rsq_f32_e32 v35, v35
	s_nop 0
	v_mul_f32_e32 v36, 0x45800000, v35
	v_cndmask_b32_e64 v118, v35, v36, s[48:49]
	v_mul_f32_e32 v35, 0x4b800000, v34
	v_cndmask_b32_e32 v34, v34, v35, vcc
	v_rsq_f32_e32 v34, v34
	s_nop 0
	v_mul_f32_e32 v35, 0x45800000, v34
	v_cndmask_b32_e32 v114, v34, v35, vcc
	s_and_saveexec_b64 s[48:49], s[40:41]
	s_cbranch_execz .LBB0_727
	v_cndmask_b32_e64 v34, v110, v104, s[46:47]
	v_cndmask_b32_e64 v34, v34, v102, s[44:45]
	v_cndmask_b32_e64 v34, v34, v0, s[42:43]
	v_cndmask_b32_e64 v0, v114, v118, s[46:47]
	v_add_u32_e32 v36, s4, v103
	v_cndmask_b32_e64 v0, v0, v112, s[44:45]
	v_ashrrev_i32_e32 v37, 31, v36
	v_cndmask_b32_e64 v35, v0, v116, s[42:43]
	v_lshl_add_u64 v[36:37], v[36:37], 3, s[8:9]
	global_store_dwordx2 v[36:37], v[34:35], off
